# v52 + diff loops: waves 4-7 issue next-tile K/V DMA batch right after their early barrier instead of at loop top
# speedup vs baseline: 1.0340x; 1.0026x over previous
; #define SBAR() __builtin_amdgcn_sched_barrier(0)
; DI int v_rd_base(int lane) { return ((lane & 3) << 3) | (((lane >> 2) & 3) << 6) | (((lane >> 4) & 1) << 5) | (((lane >> 5) & 1) << 8); }
; #define ATT_DMA_K(t) do { const bf16_t* kg_ = Kh + (size_t)(t) * 64 * LDK; LAS unsigned char* sb_ = lds + ((t) & 3) * KBUF; \
;     _Pragma("unroll") for (int i_ = 0; i_ < NKP; ++i_) __builtin_amdgcn_global_load_lds((const unsigned*)(kg_ + kgo[i_]), (LAS unsigned*)(sb_ + (wid + 8 * i_) * 1024), 16, 0, 0); } while (0)
; template <int DQK, int MODE, int LDQ, int LDK, int LDV> ...
;     ...
;     float l_reg = 0.f; f32x16 o[4];
; #pragma unroll
;     for (int d = 0; d < 4; ++d)
; #pragma unroll
;         for (int r = 0; r < 16; ++r) o[d][r] = 0.f;
;     int kgo[NKP], vgo[2];
; #pragma unroll
;     for (int i = 0; i < NKP; ++i) { const int L = (wid + 8 * i) * 64 + lane, row = L / CPR, slot = L % CPR, cc = (slot & ~7) | ((slot & 7) ^ ((row >> 1) & 7)); kgo[i] = row * LDK + cc * 8; }
; #pragma unroll
;     for (int i = 0; i < 2; ++i) { const int L = (2 * wid + i) * 64 + lane, st = L >> 5, w5 = L & 31, kk = (st >> 2) * 8 + (w5 >> 2), c = (st & 3) * 32 + (w5 & 3) * 8;
;         const int k = (kk & ~0xC) | ((kk & 4) << 1) | ((kk & 8) >> 1); vgo[i] = k * LDV + c; }
;     ...
;     const int qlo = q0 + wid * 32, qpos = qlo + r32;
;     const int tL = MODE == 0 ? 0 : (qlo >= 191 ? (qlo - 127) >> 6 : 0), tR = MODE == 0 ? NT : min(NT, (qlo + 222) >> 6);
;     float fL = 1.f, fR = 1.f; if constexpr (MODE != 0) { fL = __builtin_amdgcn_exp2f(bt[0]); fR = __builtin_amdgcn_exp2f(-bt[448]); }
;     ...
;     const int vbase = (int)(unsigned)(size_t)lds + V_OFF + v_rd_base(lane);
;     ...
;     constexpr int NDA = ND0 > 6 ? 6 : ND0;
;     ...
;     f32x16 pA, pB; bf16x8 pa0, pa1;
;     int v0 = 0, v1 = 1, v2 = 2;
;     ATT_TOP(NKP + 2);
;     { bf16x8 kf[NDA]; k_reads<DQK, 0, NDA>(kf, lds, 0, r32, hi); ATT_LGKM0(); qk_mma<0, NDA>(pA, kf, qr);
;       if constexpr (ND0 > NDA) { bf16x8 kg[ND0 - NDA]; k_reads<DQK, NDA, ND0>(kg, lds, 0, r32, hi); ATT_LGKM0(); qk_mma<NDA, ND0>(pA, kg, qr); }
;       ATT_BIAS(pA, 0, 0); }
;     if (wid >= 4) __builtin_amdgcn_s_setprio(1);
;     for (int j = 0; j < NT; ++j) {
;         if (j + 2 < NT) ATT_TOP(NKP + 2); else ATT_TOP(0);
;         if (j + 3 < NT) ATT_DMA_K(j + 3);
;         if (j + 2 < NT) ATT_DMA_V(j + 2, v2);
;         ATT_SEG(j); SBAR();
.LBB0_1919:
	s_lshl_b32 s87, s86, 7
	s_and_b32 s54, s0, 0xffffffc0
	s_min_i32 s97, s58, 64
	s_and_b32 s92, s73, 0xf00
	s_cmp_gt_i32 s55, 0
	s_cselect_b64 s[4:5], -1, 0
	s_add_i32 s93, 0, 0x18000
	s_add_i32 s1, s92, s94
	s_add_u32 s90, s2, s84
	v_add_lshl_u32 v2, s1, v2, 2
	s_addc_u32 s91, s3, 0
	v_readlane_b32 s1, v255, 6
	s_add_u32 s2, s1, s90
	s_addc_u32 s3, s76, s91
	s_add_i32 s7, s7, s6
	v_lshl_add_u64 v[100:101], v[0:1], 1, s[2:3]
	v_add3_u32 v0, s7, v6, v4
	v_lshl_or_b32 v0, v0, 11, v3
	v_and_b32_e32 v7, 63, v7
	v_add_u32_e32 v0, v0, v5
	s_add_u32 s2, s77, s90
	v_exp_f32_e32 v112, v9
	v_lshlrev_b32_e32 v8, 3, v7
	v_lshlrev_b32_e32 v9, 4, v7
	v_lshlrev_b32_e32 v7, 1, v7
	v_ashrrev_i32_e32 v1, 31, v0
	s_addc_u32 s3, s78, s91
	v_exp_f32_e64 v113, -v10
	v_and_b32_e32 v7, 32, v7
	v_lshl_add_u64 v[102:103], v[0:1], 1, s[2:3]
	v_add_u32_e32 v0, 64, v0
	v_and_b32_e32 v9, 0xc0, v9
	v_and_or_b32 v7, v8, s66, v7
	v_sub_u32_e32 v2, v130, v2
	v_ashrrev_i32_e32 v1, 31, v0
	v_mov_b32_e32 v14, v131
	v_mov_b32_e32 v15, v131
	v_add3_u32 v106, v9, s93, v7
	v_add_u32_e32 v119, 0, v2
	v_lshl_add_u64 v[104:105], v[0:1], 1, s[2:3]
	v_mov_b32_e32 v0, v131
	v_mov_b32_e32 v1, v131
	v_mov_b32_e32 v2, v131
	v_mov_b32_e32 v3, v131
	v_mov_b32_e32 v4, v131
	v_mov_b32_e32 v5, v131
	v_mov_b32_e32 v6, v131
	v_mov_b32_e32 v7, v131
	v_mov_b32_e32 v8, v131
	v_mov_b32_e32 v9, v131
	v_mov_b32_e32 v10, v131
	v_mov_b32_e32 v11, v131
	v_mov_b32_e32 v12, v131
	v_mov_b32_e32 v13, v131
	v_mov_b64_e32 v[62:63], v[14:15]
	v_mov_b64_e32 v[46:47], v[14:15]
	v_mov_b64_e32 v[30:31], v[14:15]
	s_mov_b32 s0, 1
	s_mov_b32 s23, 0
	s_mov_b32 s96, 2
	s_sub_i32 s62, 0, s55
	s_sub_i32 s6, 0, s97
	v_mov_b32_e32 v120, 0
	s_movk_i32 s7, 0xc300
	s_movk_i32 s22, 0x6000
	v_mov_b64_e32 v[60:61], v[12:13]
	v_mov_b64_e32 v[58:59], v[10:11]
	v_mov_b64_e32 v[56:57], v[8:9]
	v_mov_b64_e32 v[54:55], v[6:7]
	v_mov_b64_e32 v[52:53], v[4:5]
	v_mov_b64_e32 v[50:51], v[2:3]
	v_mov_b64_e32 v[48:49], v[0:1]
	v_mov_b64_e32 v[44:45], v[12:13]
	v_mov_b64_e32 v[42:43], v[10:11]
	v_mov_b64_e32 v[40:41], v[8:9]
	v_mov_b64_e32 v[38:39], v[6:7]
	v_mov_b64_e32 v[36:37], v[4:5]
	v_mov_b64_e32 v[34:35], v[2:3]
	v_mov_b64_e32 v[32:33], v[0:1]
	v_mov_b64_e32 v[28:29], v[12:13]
	v_mov_b64_e32 v[26:27], v[10:11]
	v_mov_b64_e32 v[24:25], v[8:9]
	v_mov_b64_e32 v[22:23], v[6:7]
	v_mov_b64_e32 v[20:21], v[4:5]
	v_mov_b64_e32 v[18:19], v[2:3]
	v_mov_b64_e32 v[16:17], v[0:1]
	s_mov_b32 s64, 1
	s_cmp_lt_u32 s33, 0x100
	s_cbranch_scc1 .Lstg_d0_pre_9
	s_waitcnt vmcnt(3)
	s_barrier
	s_and_b32 s1, s22, 0x6000
	s_add_i32 m0, s59, s1
	s_lshl_b32 s1, s96, 14
	s_add_i32 s1, s95, s1
	global_load_lds_dwordx4 v[100:101], off
	s_add_i32 s2, s1, 0x400
	s_mov_b32 m0, s1
	s_nop 0
	global_load_lds_dwordx4 v[102:103], off
	s_mov_b32 m0, s2
	s_nop 0
	global_load_lds_dwordx4 v[104:105], off
.Lstg_d0_pre_9:
.LBB0_1920:
	s_and_b32 s1, s22, 0x6000
	s_add_i32 m0, s59, s1
	s_lshl_b32 s1, s96, 14
	s_cmp_lt_u32 s33, 0x100
	s_cbranch_scc0 .Lstg_d0_top_10
	s_waitcnt vmcnt(3)
	s_barrier
	s_add_i32 s1, s95, s1
	global_load_lds_dwordx4 v[100:101], off
	s_add_i32 s2, s1, 0x400
	s_mov_b32 m0, s1
	s_nop 0
	global_load_lds_dwordx4 v[102:103], off
	s_mov_b32 m0, s2
	s_nop 0
	global_load_lds_dwordx4 v[104:105], off
.Lstg_d0_top_10:
	s_setprio 0
	s_add_i32 s1, s62, s0
	s_add_i32 s74, s6, s0
	s_cmp_eq_u32 s1, 1
	s_cselect_b64 s[2:3], -1, 0
	s_and_b64 vcc, s[4:5], s[2:3]
	s_cmp_eq_u32 s74, 1
	s_cselect_b64 s[2:3], -1, 0
	s_or_b64 vcc, s[2:3], vcc
	s_andn2_b64 vcc, exec, vcc
	s_mov_b32 s1, s23
	s_cbranch_vccnz .LBB0_1922
	v_cndmask_b32_e64 v122, v112, v113, s[2:3]
	v_pk_mul_f32 v[14:15], v[14:15], v[122:123] op_sel_hi:[1,0]
	v_pk_mul_f32 v[12:13], v[12:13], v[122:123] op_sel_hi:[1,0]
	v_pk_mul_f32 v[10:11], v[10:11], v[122:123] op_sel_hi:[1,0]
	v_pk_mul_f32 v[8:9], v[8:9], v[122:123] op_sel_hi:[1,0]
	v_pk_mul_f32 v[6:7], v[6:7], v[122:123] op_sel_hi:[1,0]
	v_pk_mul_f32 v[4:5], v[4:5], v[122:123] op_sel_hi:[1,0]
	v_pk_mul_f32 v[2:3], v[2:3], v[122:123] op_sel_hi:[1,0]
	v_pk_mul_f32 v[0:1], v[0:1], v[122:123] op_sel_hi:[1,0]
	v_pk_mul_f32 v[62:63], v[62:63], v[122:123] op_sel_hi:[1,0]
	v_pk_mul_f32 v[60:61], v[60:61], v[122:123] op_sel_hi:[1,0]
	v_pk_mul_f32 v[58:59], v[58:59], v[122:123] op_sel_hi:[1,0]
	v_pk_mul_f32 v[56:57], v[56:57], v[122:123] op_sel_hi:[1,0]
	v_pk_mul_f32 v[54:55], v[54:55], v[122:123] op_sel_hi:[1,0]
	v_pk_mul_f32 v[52:53], v[52:53], v[122:123] op_sel_hi:[1,0]
	v_pk_mul_f32 v[50:51], v[50:51], v[122:123] op_sel_hi:[1,0]
	v_pk_mul_f32 v[48:49], v[48:49], v[122:123] op_sel_hi:[1,0]
	v_pk_mul_f32 v[46:47], v[46:47], v[122:123] op_sel_hi:[1,0]
	v_pk_mul_f32 v[44:45], v[44:45], v[122:123] op_sel_hi:[1,0]
	v_pk_mul_f32 v[42:43], v[42:43], v[122:123] op_sel_hi:[1,0]
	v_pk_mul_f32 v[40:41], v[40:41], v[122:123] op_sel_hi:[1,0]
	v_pk_mul_f32 v[38:39], v[38:39], v[122:123] op_sel_hi:[1,0]
	v_pk_mul_f32 v[36:37], v[36:37], v[122:123] op_sel_hi:[1,0]
	v_pk_mul_f32 v[34:35], v[34:35], v[122:123] op_sel_hi:[1,0]
	v_pk_mul_f32 v[32:33], v[32:33], v[122:123] op_sel_hi:[1,0]
	v_pk_mul_f32 v[30:31], v[30:31], v[122:123] op_sel_hi:[1,0]
	v_pk_mul_f32 v[28:29], v[28:29], v[122:123] op_sel_hi:[1,0]
	v_pk_mul_f32 v[26:27], v[26:27], v[122:123] op_sel_hi:[1,0]
	v_pk_mul_f32 v[24:25], v[24:25], v[122:123] op_sel_hi:[1,0]
	v_pk_mul_f32 v[22:23], v[22:23], v[122:123] op_sel_hi:[1,0]
	v_pk_mul_f32 v[20:21], v[20:21], v[122:123] op_sel_hi:[1,0]
	v_pk_mul_f32 v[18:19], v[18:19], v[122:123] op_sel_hi:[1,0]
	v_pk_mul_f32 v[16:17], v[16:17], v[122:123] op_sel_hi:[1,0]
	v_mul_f32_e32 v120, v120, v122

; #define LAS __attribute__((address_space(3)))
; DI void expsum(f32x16& p, float& l_reg, bf16x8& pa0, bf16x8& pa1) {
; #pragma unroll
;     for (int r = 0; r < 16; ++r) p[r] = __builtin_amdgcn_exp2f(p[r]);
;     float ps = 0.f;
; #pragma unroll
;     for (int r = 0; r < 16; ++r) ps += p[r];
;     l_reg += ps; asm volatile("" : "+v"(l_reg));
;     ...
;     ATT_PK4(p, 0, pa0); ATT_PK4(p, 8, pa1);
;     ...
; }
; DI int v_rd_base(int lane) { return ((lane & 3) << 3) | (((lane >> 2) & 3) << 6) | (((lane >> 4) & 1) << 5) | (((lane >> 5) & 1) << 8); }
; template <int OFF> DI s16x4 tr_read(int vb) { s16x4 r; asm volatile("ds_read_b64_tr_b16 %0, %1 offset:%2" : "=&v"(r) : "v"(vb), "i"(OFF) : "memory"); return r; }
; template <int H> DI void v_reads(s16x4* vf, int vb) {
;     vf[0] = tr_read<v_rd_off(0, 2 * H, 0)>(vb); vf[1] = tr_read<v_rd_off(0, 2 * H, 1)>(vb); vf[2] = tr_read<v_rd_off(0, 2 * H + 1, 0)>(vb); vf[3] = tr_read<v_rd_off(0, 2 * H + 1, 1)>(vb);
;     vf[4] = tr_read<v_rd_off(1, 2 * H, 0)>(vb); vf[5] = tr_read<v_rd_off(1, 2 * H, 1)>(vb); vf[6] = tr_read<v_rd_off(1, 2 * H + 1, 0)>(vb); vf[7] = tr_read<v_rd_off(1, 2 * H + 1, 1)>(vb);
;     vf[8] = tr_read<v_rd_off(2, 2 * H, 0)>(vb); vf[9] = tr_read<v_rd_off(2, 2 * H, 1)>(vb); vf[10] = tr_read<v_rd_off(2, 2 * H + 1, 0)>(vb); vf[11] = tr_read<v_rd_off(2, 2 * H + 1, 1)>(vb);
;     vf[12] = tr_read<v_rd_off(3, 2 * H, 0)>(vb); vf[13] = tr_read<v_rd_off(3, 2 * H, 1)>(vb); vf[14] = tr_read<v_rd_off(3, 2 * H + 1, 0)>(vb); vf[15] = tr_read<v_rd_off(3, 2 * H + 1, 1)>(vb);
; }
; DI void pv_mma(f32x16* o, const s16x4* vf, bf16x8 pa0, bf16x8 pa1) {
;     ...
; #pragma unroll
;     for (int d0 = 0; d0 < 4; ++d0) {
;         o[d0] = __builtin_amdgcn_mfma_f32_32x32x16_bf16(pa0, ATT_PK(vf[4 * d0], vf[4 * d0 + 1]), o[d0], 0, 0, 0);
;         o[d0] = __builtin_amdgcn_mfma_f32_32x32x16_bf16(pa1, ATT_PK(vf[4 * d0 + 2], vf[4 * d0 + 3]), o[d0], 0, 0, 0); }
;     ...
; }
; template <int DQK, int D0A, int D0B> DI void k_reads(bf16x8* kf, const LAS unsigned char* Ks, int half, int r32, int hi) {
; #pragma unroll
;     for (int d0 = D0A; d0 < D0B; ++d0) kf[d0 - D0A] = *(const LAS bf16x8*)(Ks + half * (32 * DQK * 2) + kswz<DQK>(r32, (d0 * 16 + hi * 8) * 2));
; }
; template <int D0A, int D0B> DI void qk_mma(f32x16& p, const bf16x8* kf, const bf16x8* qr) {
; #pragma unroll
;     for (int d0 = D0A; d0 < D0B; ++d0) {
.LBB0_1924:
	s_add_i32 s3, s22, 0xffffc000
	s_and_b32 s3, s3, 0x6000
	v_add_u32_e32 v123, s3, v114
	v_add_u32_e32 v140, v123, v118
	v_add_u32_e32 v136, v123, v117
	v_add_u32_e32 v132, v123, v116
	v_add_u32_e32 v123, v123, v115
	ds_read_b128 v[124:127], v123
	ds_read_b128 v[132:135], v132
	ds_read_b128 v[136:139], v136
	ds_read_b128 v[140:143], v140
	ds_read_b64_tr_b16 v[144:145], v121 offset:0x2000
	ds_read_b64_tr_b16 v[146:147], v121 offset:0x2800
	ds_read_b64_tr_b16 v[148:149], v121 offset:0x3000
	ds_read_b64_tr_b16 v[150:151], v121 offset:0x3800
	ds_read_b64_tr_b16 v[152:153], v121 offset:0x2200
	ds_read_b64_tr_b16 v[154:155], v121 offset:0x2a00
	ds_read_b64_tr_b16 v[156:157], v121 offset:0x3200
	ds_read_b64_tr_b16 v[158:159], v121 offset:0x3a00
	ds_read_b64_tr_b16 v[162:163], v121 offset:0x2400
	ds_read_b64_tr_b16 v[164:165], v121 offset:0x2c00
	ds_read_b64_tr_b16 v[166:167], v121 offset:0x3400
	ds_read_b64_tr_b16 v[168:169], v121 offset:0x3c00
	ds_read_b64_tr_b16 v[170:171], v121 offset:0x2600
	ds_read_b64_tr_b16 v[172:173], v121 offset:0x2e00
	ds_read_b64_tr_b16 v[174:175], v121 offset:0x3600
	ds_read_b64_tr_b16 v[176:177], v121 offset:0x3e00
	s_setprio 2
	v_exp_f32_e32 v64, v64
	v_exp_f32_e32 v65, v65
	v_exp_f32_e32 v66, v66
	v_exp_f32_e32 v67, v67
	v_exp_f32_e32 v68, v68
	v_exp_f32_e32 v69, v69
	v_add_f32_e32 v121, v65, v64
	v_exp_f32_e32 v70, v70
	v_add_f32_e32 v121, v66, v121
	v_exp_f32_e32 v71, v71
	v_add_f32_e32 v121, v67, v121
	v_exp_f32_e32 v72, v72
	v_add_f32_e32 v121, v68, v121
	v_exp_f32_e32 v73, v73
	v_add_f32_e32 v121, v69, v121
	v_exp_f32_e32 v74, v74
	v_add_f32_e32 v121, v70, v121
	v_exp_f32_e32 v75, v75
	v_add_f32_e32 v121, v71, v121
	v_exp_f32_e32 v76, v76
	v_add_f32_e32 v121, v72, v121
	v_exp_f32_e32 v77, v77
	v_add_f32_e32 v121, v73, v121
	v_exp_f32_e32 v78, v78
	v_add_f32_e32 v121, v74, v121
	v_exp_f32_e32 v79, v79
	v_add_f32_e32 v121, v75, v121
	v_add_f32_e32 v121, v76, v121
	v_add_f32_e32 v121, v77, v121
	v_add_f32_e32 v121, v78, v121
	v_add_f32_e32 v121, v79, v121
	v_add_f32_e32 v120, v120, v121
	v_cvt_pk_bf16_f32 v64, v64, v65
	v_cvt_pk_bf16_f32 v65, v66, v67
	v_cvt_pk_bf16_f32 v66, v68, v69
	v_cvt_pk_bf16_f32 v67, v70, v71
	v_cvt_pk_bf16_f32 v68, v72, v73
	v_cvt_pk_bf16_f32 v69, v74, v75
	v_cvt_pk_bf16_f32 v70, v76, v77
	v_cvt_pk_bf16_f32 v71, v78, v79
	s_nop 0
	v_permlane32_swap_b32_e32 v64, v66
	v_permlane32_swap_b32_e32 v65, v67
	v_permlane32_swap_b32_e32 v68, v70
	v_permlane32_swap_b32_e32 v69, v71
	s_waitcnt lgkmcnt(0)
	s_setprio 1
	s_cmp_lt_u32 s33, 0x100
	s_cbranch_scc1 .Lstg_d0_mid_11
	s_waitcnt vmcnt(3)
	s_barrier
	s_cmp_lg_u32 s7, 0xffffff00
	s_cbranch_scc0 .Lstg_d0_noearly
	s_add_i32 s99, s22, 0x2000
	s_and_b32 s99, s99, 0x6000
	s_add_i32 m0, s59, s99
	v_lshl_add_u64 v[196:197], v[100:101], 0, s[8:9]
	v_lshl_add_u64 v[198:199], v[102:103], 0, s[8:9]
	v_lshl_add_u64 v[200:201], v[104:105], 0, s[8:9]
	global_load_lds_dwordx4 v[196:197], off
	s_lshl_b32 s99, s1, 14
	s_add_i32 s99, s95, s99
	s_mov_b32 m0, s99
	s_nop 0
	global_load_lds_dwordx4 v[198:199], off
	s_add_i32 m0, s99, 0x400
	s_nop 0
	global_load_lds_dwordx4 v[200:201], off
.Lstg_d0_noearly:
.Lstg_d0_mid_11:
	v_mfma_f32_32x32x16_bf16 v[0:15], v[64:67], v[144:147], v[0:15]
	s_cmp_lt_i32 s0, s55
	s_cselect_b64 s[74:75], -1, 0
	s_cmp_ge_i32 s0, s97
	s_cselect_b64 vcc, -1, 0
	s_or_b64 s[74:75], s[74:75], vcc
	s_and_b64 vcc, exec, s[74:75]
	v_mfma_f32_32x32x16_bf16 v[48:63], v[64:67], v[152:155], v[48:63]
	v_mfma_f32_32x32x16_bf16 v[32:47], v[64:67], v[162:165], v[32:47]
	v_mfma_f32_32x32x16_bf16 v[16:31], v[64:67], v[170:173], v[16:31]
	v_mfma_f32_32x32x16_bf16 v[0:15], v[68:71], v[148:151], v[0:15]
	v_mfma_f32_32x32x16_bf16 v[48:63], v[68:71], v[156:159], v[48:63]
	v_mfma_f32_32x32x16_bf16 v[32:47], v[68:71], v[166:169], v[32:47]
	v_mfma_f32_32x32x16_bf16 v[16:31], v[68:71], v[174:177], v[16:31]
	v_mfma_f32_32x32x16_bf16 v[64:79], v[124:127], v[92:95], 0
	v_mfma_f32_32x32x16_bf16 v[64:79], v[132:135], v[88:91], v[64:79]
	v_mfma_f32_32x32x16_bf16 v[64:79], v[136:139], v[84:87], v[64:79]
	v_mfma_f32_32x32x16_bf16 v[64:79], v[140:143], v[80:83], v[64:79]
	s_cbranch_vccnz .LBB0_1926
	v_add_u32_e32 v136, 0x28988, v122
	v_add_u32_e32 v138, 0x289a0, v122
	v_add_u32_e32 v140, 0x289a8, v122
	v_add_u32_e32 v123, 0x289c0, v122
	v_add_u32_e32 v124, 0x289c8, v122
	v_add_u32_e32 v126, 0x289e0, v122
	v_add_u32_e32 v132, 0x289e8, v122
	v_add_u32_e32 v121, 0x28980, v122
	ds_read2_b32 v[122:123], v123 offset1:1
	ds_read2_b32 v[124:125], v124 offset1:1
	ds_read2_b32 v[126:127], v126 offset1:1
	ds_read2_b32 v[132:133], v132 offset1:1
	ds_read2_b32 v[134:135], v121 offset1:1
	ds_read2_b32 v[136:137], v136 offset1:1
	ds_read2_b32 v[138:139], v138 offset1:1
	ds_read2_b32 v[140:141], v140 offset1:1
	s_waitcnt lgkmcnt(0)
	v_pk_add_f32 v[78:79], v[78:79], v[132:133]
	v_pk_add_f32 v[76:77], v[76:77], v[126:127]
	v_pk_add_f32 v[74:75], v[74:75], v[124:125]
	v_pk_add_f32 v[72:73], v[72:73], v[122:123]
	v_pk_add_f32 v[70:71], v[70:71], v[140:141]
	v_pk_add_f32 v[68:69], v[68:69], v[138:139]
	v_pk_add_f32 v[66:67], v[66:67], v[136:137]
	v_pk_add_f32 v[64:65], v[64:65], v[134:135]

; template <int DQK, int MODE, int LDQ, int LDK, int LDV> ...
;     ...
;     float l_reg = 0.f; f32x16 o[4];
; #pragma unroll
;     for (int d = 0; d < 4; ++d)
; #pragma unroll
;         for (int r = 0; r < 16; ++r) o[d][r] = 0.f;
;     int kgo[NKP], vgo[2];
; #pragma unroll
;     for (int i = 0; i < NKP; ++i) { const int L = (wid + 8 * i) * 64 + lane, row = L / CPR, slot = L % CPR, cc = (slot & ~7) | ((slot & 7) ^ ((row >> 1) & 7)); kgo[i] = row * LDK + cc * 8; }
; #pragma unroll
;     for (int i = 0; i < 2; ++i) { const int L = (2 * wid + i) * 64 + lane, st = L >> 5, w5 = L & 31, kk = (st >> 2) * 8 + (w5 >> 2), c = (st & 3) * 32 + (w5 & 3) * 8;
;         const int k = (kk & ~0xC) | ((kk & 4) << 1) | ((kk & 8) >> 1); vgo[i] = k * LDV + c; }
;     ...
;     ATT_DMA_K(0); ATT_DMA_K(1); ATT_DMA_V(0, 0); ATT_DMA_K(2); ATT_DMA_V(1, 1);
;     bf16x8 qr[ND0];
;     { const bf16_t* Qw = Qb + (size_t)(wid * 32 + r32) * LDQ + hi * 8;
; #pragma unroll
;       for (int d0 = 0; d0 < ND0; ++d0) qr[d0] = *(const bf16x8*)(Qw + d0 * 16);
;       if constexpr (MODE == 0) {
;           float ss = 0.f;
; #pragma unroll
;           for (int d0 = 0; d0 < ND0; ++d0)
; #pragma unroll
;               for (int j = 0; j < 8; ++j) { const float f = bf2f((unsigned short)qr[d0][j]); ss += f * f; }
;           ss = swap_sum(ss);
;           const float rstd = rsqrtf(ss * (1.f / DQK) + EPS) * C;
; #pragma unroll
;           for (int d0 = 0; d0 < ND0; ++d0) { const float* g = gq + d0 * 16 + hi * 8;
;               { float f[8]; _Pragma("unroll") for (int j = 0; j < 8; ++j) f[j] = bf2f((unsigned short)qr[d0][j]) * rstd * g[j];
;                 u32x4 w = {cvtpk(f[0], f[1]), cvtpk(f[2], f[3]), cvtpk(f[4], f[5]), cvtpk(f[6], f[7])}; qr[d0] = __builtin_bit_cast(bf16x8, w); asm volatile("" ::: "memory"); } }
;       } }
;     const int qlo = q0 + wid * 32, qpos = qlo + r32;
;     const int tL = MODE == 0 ? 0 : (qlo >= 191 ? (qlo - 127) >> 6 : 0), tR = MODE == 0 ? NT : min(NT, (qlo + 222) >> 6);
;     float fL = 1.f, fR = 1.f; if constexpr (MODE != 0) { fL = __builtin_amdgcn_exp2f(bt[0]); fR = __builtin_amdgcn_exp2f(-bt[448]); }
;     ...
;     const int vbase = (int)(unsigned)(size_t)lds + V_OFF + v_rd_base(lane);
;     ...
;     for (int j = 0; j < NT; ++j) {
;         if (j + 2 < NT) ATT_TOP(NKP + 2); else ATT_TOP(0);
;         if (j + 3 < NT) ATT_DMA_K(j + 3);
;         if (j + 2 < NT) ATT_DMA_V(j + 2, v2);
.LBB0_1950:
	s_and_b32 s44, s0, 0xffffffc0
	s_min_i32 s52, s45, 64
	s_cmp_gt_i32 s47, 0
	s_cselect_b64 s[4:5], -1, 0
	s_add_i32 s92, s92, s46
	s_add_u32 s6, s79, s90
	s_addc_u32 s7, s80, s91
	s_add_i32 s3, s3, s2
	v_lshl_add_u64 v[100:101], v[0:1], 1, s[6:7]
	v_add3_u32 v0, s3, v6, v4
	v_lshl_or_b32 v0, v0, 11, v3
	v_and_b32_e32 v7, 63, v7
	v_add_u32_e32 v0, v0, v5
	s_add_u32 s2, s77, s90
	v_exp_f32_e32 v112, v9
	v_lshlrev_b32_e32 v8, 3, v7
	v_lshlrev_b32_e32 v9, 4, v7
	v_lshlrev_b32_e32 v7, 1, v7
	v_ashrrev_i32_e32 v1, 31, v0
	s_addc_u32 s3, s78, s91
	v_exp_f32_e64 v113, -v10
	v_and_b32_e32 v7, 32, v7
	v_add_lshl_u32 v2, s92, v2, 2
	v_lshl_add_u64 v[102:103], v[0:1], 1, s[2:3]
	v_add_u32_e32 v0, 64, v0
	v_and_b32_e32 v9, 0xc0, v9
	v_and_or_b32 v7, v8, s66, v7
	v_sub_u32_e32 v2, v130, v2
	v_ashrrev_i32_e32 v1, 31, v0
	v_mov_b32_e32 v14, v131
	v_mov_b32_e32 v15, v131
	v_add3_u32 v106, v9, s93, v7
	v_add_u32_e32 v119, 0, v2
	v_lshl_add_u64 v[104:105], v[0:1], 1, s[2:3]
	v_mov_b32_e32 v0, v131
	v_mov_b32_e32 v1, v131
	v_mov_b32_e32 v2, v131
	v_mov_b32_e32 v3, v131
	v_mov_b32_e32 v4, v131
	v_mov_b32_e32 v5, v131
	v_mov_b32_e32 v6, v131
	v_mov_b32_e32 v7, v131
	v_mov_b32_e32 v8, v131
	v_mov_b32_e32 v9, v131
	v_mov_b32_e32 v10, v131
	v_mov_b32_e32 v11, v131
	v_mov_b32_e32 v12, v131
	v_mov_b32_e32 v13, v131
	v_mov_b64_e32 v[62:63], v[14:15]
	v_mov_b64_e32 v[30:31], v[14:15]
	v_mov_b64_e32 v[46:47], v[14:15]
	s_mov_b32 s0, 1
	s_mov_b32 s62, 0
	s_mov_b32 s1, 2
	s_sub_i32 s53, 0, s47
	s_sub_i32 s6, 0, s52
	v_mov_b32_e32 v120, 0
	s_movk_i32 s7, 0xc300
	s_movk_i32 s22, 0x6000
	v_mov_b64_e32 v[60:61], v[12:13]
	v_mov_b64_e32 v[58:59], v[10:11]
	v_mov_b64_e32 v[56:57], v[8:9]
	v_mov_b64_e32 v[54:55], v[6:7]
	v_mov_b64_e32 v[52:53], v[4:5]
	v_mov_b64_e32 v[50:51], v[2:3]
	v_mov_b64_e32 v[48:49], v[0:1]
	v_mov_b64_e32 v[28:29], v[12:13]
	v_mov_b64_e32 v[26:27], v[10:11]
	v_mov_b64_e32 v[24:25], v[8:9]
	v_mov_b64_e32 v[22:23], v[6:7]
	v_mov_b64_e32 v[20:21], v[4:5]
	v_mov_b64_e32 v[18:19], v[2:3]
	v_mov_b64_e32 v[16:17], v[0:1]
	v_mov_b64_e32 v[44:45], v[12:13]
	v_mov_b64_e32 v[42:43], v[10:11]
	v_mov_b64_e32 v[40:41], v[8:9]
	v_mov_b64_e32 v[38:39], v[6:7]
	v_mov_b64_e32 v[36:37], v[4:5]
	v_mov_b64_e32 v[34:35], v[2:3]
	v_mov_b64_e32 v[32:33], v[0:1]
	s_mov_b32 s49, 1
	s_cmp_lt_u32 s33, 0x100
	s_cbranch_scc1 .Lstg_d1_pre_17
	s_waitcnt vmcnt(3)
	s_barrier
	s_and_b32 s2, s22, 0x6000
	s_add_i32 m0, s94, s2
	s_lshl_b32 s2, s1, 14
	s_add_i32 s2, s48, s2
	global_load_lds_dwordx4 v[100:101], off
	s_add_i32 s3, s2, 0x400
	s_mov_b32 m0, s2
	s_nop 0
	global_load_lds_dwordx4 v[102:103], off
	s_mov_b32 m0, s3
	s_nop 0
	global_load_lds_dwordx4 v[104:105], off
.Lstg_d1_pre_17:
.LBB0_1951:
	s_and_b32 s2, s22, 0x6000
	s_add_i32 m0, s94, s2
	s_lshl_b32 s2, s1, 14
	s_cmp_lt_u32 s33, 0x100
	s_cbranch_scc0 .Lstg_d1_top_18
	s_waitcnt vmcnt(3)
	s_barrier
	s_add_i32 s2, s48, s2
	global_load_lds_dwordx4 v[100:101], off
	s_add_i32 s3, s2, 0x400
	s_mov_b32 m0, s2
	s_nop 0
	global_load_lds_dwordx4 v[102:103], off
	s_mov_b32 m0, s3
	s_nop 0
	global_load_lds_dwordx4 v[104:105], off
.Lstg_d1_top_18:
	s_setprio 0
	s_add_i32 s2, s53, s0
	s_add_i32 s23, s6, s0
	s_cmp_eq_u32 s2, 1
	s_cselect_b64 s[2:3], -1, 0
	s_and_b64 s[74:75], s[4:5], s[2:3]
	s_cmp_eq_u32 s23, 1
	s_cselect_b64 s[2:3], -1, 0
	s_or_b64 s[74:75], s[2:3], s[74:75]
	s_andn2_b64 vcc, exec, s[74:75]
	s_mov_b32 s23, s62
	s_cbranch_vccnz .LBB0_1953
	v_cndmask_b32_e64 v122, v112, v113, s[2:3]
	v_pk_mul_f32 v[14:15], v[14:15], v[122:123] op_sel_hi:[1,0]
	v_pk_mul_f32 v[12:13], v[12:13], v[122:123] op_sel_hi:[1,0]
	v_pk_mul_f32 v[10:11], v[10:11], v[122:123] op_sel_hi:[1,0]
	v_pk_mul_f32 v[8:9], v[8:9], v[122:123] op_sel_hi:[1,0]
	v_pk_mul_f32 v[6:7], v[6:7], v[122:123] op_sel_hi:[1,0]
	v_pk_mul_f32 v[4:5], v[4:5], v[122:123] op_sel_hi:[1,0]
	v_pk_mul_f32 v[2:3], v[2:3], v[122:123] op_sel_hi:[1,0]
	v_pk_mul_f32 v[0:1], v[0:1], v[122:123] op_sel_hi:[1,0]
	v_pk_mul_f32 v[62:63], v[62:63], v[122:123] op_sel_hi:[1,0]
	v_pk_mul_f32 v[60:61], v[60:61], v[122:123] op_sel_hi:[1,0]
	v_pk_mul_f32 v[58:59], v[58:59], v[122:123] op_sel_hi:[1,0]
	v_pk_mul_f32 v[56:57], v[56:57], v[122:123] op_sel_hi:[1,0]
	v_pk_mul_f32 v[54:55], v[54:55], v[122:123] op_sel_hi:[1,0]
	v_pk_mul_f32 v[52:53], v[52:53], v[122:123] op_sel_hi:[1,0]
	v_pk_mul_f32 v[50:51], v[50:51], v[122:123] op_sel_hi:[1,0]
	v_pk_mul_f32 v[48:49], v[48:49], v[122:123] op_sel_hi:[1,0]
	v_pk_mul_f32 v[30:31], v[30:31], v[122:123] op_sel_hi:[1,0]
	v_pk_mul_f32 v[28:29], v[28:29], v[122:123] op_sel_hi:[1,0]
	v_pk_mul_f32 v[26:27], v[26:27], v[122:123] op_sel_hi:[1,0]
	v_pk_mul_f32 v[24:25], v[24:25], v[122:123] op_sel_hi:[1,0]
	v_pk_mul_f32 v[22:23], v[22:23], v[122:123] op_sel_hi:[1,0]
	v_pk_mul_f32 v[20:21], v[20:21], v[122:123] op_sel_hi:[1,0]
	v_pk_mul_f32 v[18:19], v[18:19], v[122:123] op_sel_hi:[1,0]
	v_pk_mul_f32 v[16:17], v[16:17], v[122:123] op_sel_hi:[1,0]
	v_pk_mul_f32 v[46:47], v[46:47], v[122:123] op_sel_hi:[1,0]
	v_pk_mul_f32 v[44:45], v[44:45], v[122:123] op_sel_hi:[1,0]
	v_pk_mul_f32 v[42:43], v[42:43], v[122:123] op_sel_hi:[1,0]
	v_pk_mul_f32 v[40:41], v[40:41], v[122:123] op_sel_hi:[1,0]
	v_pk_mul_f32 v[38:39], v[38:39], v[122:123] op_sel_hi:[1,0]
	v_pk_mul_f32 v[36:37], v[36:37], v[122:123] op_sel_hi:[1,0]
	v_pk_mul_f32 v[34:35], v[34:35], v[122:123] op_sel_hi:[1,0]
	v_pk_mul_f32 v[32:33], v[32:33], v[122:123] op_sel_hi:[1,0]
	v_mul_f32_e32 v120, v120, v122

; #define LAS __attribute__((address_space(3)))
; DI void expsum(f32x16& p, float& l_reg, bf16x8& pa0, bf16x8& pa1) {
; #pragma unroll
;     for (int r = 0; r < 16; ++r) p[r] = __builtin_amdgcn_exp2f(p[r]);
;     float ps = 0.f;
; #pragma unroll
;     for (int r = 0; r < 16; ++r) ps += p[r];
;     l_reg += ps; asm volatile("" : "+v"(l_reg));
;     ...
;     ATT_PK4(p, 0, pa0); ATT_PK4(p, 8, pa1);
;     ...
; }
; DI int v_rd_base(int lane) { return ((lane & 3) << 3) | (((lane >> 2) & 3) << 6) | (((lane >> 4) & 1) << 5) | (((lane >> 5) & 1) << 8); }
; template <int OFF> DI s16x4 tr_read(int vb) { s16x4 r; asm volatile("ds_read_b64_tr_b16 %0, %1 offset:%2" : "=&v"(r) : "v"(vb), "i"(OFF) : "memory"); return r; }
; template <int H> DI void v_reads(s16x4* vf, int vb) {
;     vf[0] = tr_read<v_rd_off(0, 2 * H, 0)>(vb); vf[1] = tr_read<v_rd_off(0, 2 * H, 1)>(vb); vf[2] = tr_read<v_rd_off(0, 2 * H + 1, 0)>(vb); vf[3] = tr_read<v_rd_off(0, 2 * H + 1, 1)>(vb);
;     vf[4] = tr_read<v_rd_off(1, 2 * H, 0)>(vb); vf[5] = tr_read<v_rd_off(1, 2 * H, 1)>(vb); vf[6] = tr_read<v_rd_off(1, 2 * H + 1, 0)>(vb); vf[7] = tr_read<v_rd_off(1, 2 * H + 1, 1)>(vb);
;     vf[8] = tr_read<v_rd_off(2, 2 * H, 0)>(vb); vf[9] = tr_read<v_rd_off(2, 2 * H, 1)>(vb); vf[10] = tr_read<v_rd_off(2, 2 * H + 1, 0)>(vb); vf[11] = tr_read<v_rd_off(2, 2 * H + 1, 1)>(vb);
;     vf[12] = tr_read<v_rd_off(3, 2 * H, 0)>(vb); vf[13] = tr_read<v_rd_off(3, 2 * H, 1)>(vb); vf[14] = tr_read<v_rd_off(3, 2 * H + 1, 0)>(vb); vf[15] = tr_read<v_rd_off(3, 2 * H + 1, 1)>(vb);
; }
; DI void pv_mma(f32x16* o, const s16x4* vf, bf16x8 pa0, bf16x8 pa1) {
;     ...
; #pragma unroll
;     for (int d0 = 0; d0 < 4; ++d0) {
;         o[d0] = __builtin_amdgcn_mfma_f32_32x32x16_bf16(pa0, ATT_PK(vf[4 * d0], vf[4 * d0 + 1]), o[d0], 0, 0, 0);
;         o[d0] = __builtin_amdgcn_mfma_f32_32x32x16_bf16(pa1, ATT_PK(vf[4 * d0 + 2], vf[4 * d0 + 3]), o[d0], 0, 0, 0); }
;     ...
; }
; template <int DQK, int D0A, int D0B> DI void k_reads(bf16x8* kf, const LAS unsigned char* Ks, int half, int r32, int hi) {
; #pragma unroll
;     for (int d0 = D0A; d0 < D0B; ++d0) kf[d0 - D0A] = *(const LAS bf16x8*)(Ks + half * (32 * DQK * 2) + kswz<DQK>(r32, (d0 * 16 + hi * 8) * 2));
; }
; template <int D0A, int D0B> DI void qk_mma(f32x16& p, const bf16x8* kf, const bf16x8* qr) {
; #pragma unroll
;     for (int d0 = D0A; d0 < D0B; ++d0) {
.LBB0_1955:
	s_add_i32 s3, s22, 0xffffc000
	s_and_b32 s3, s3, 0x6000
	v_add_u32_e32 v123, s3, v114
	v_add_u32_e32 v140, v123, v118
	v_add_u32_e32 v136, v123, v117
	v_add_u32_e32 v132, v123, v116
	v_add_u32_e32 v123, v123, v115
	ds_read_b128 v[124:127], v123
	ds_read_b128 v[132:135], v132
	ds_read_b128 v[136:139], v136
	ds_read_b128 v[140:143], v140
	ds_read_b64_tr_b16 v[144:145], v121 offset:0x2000
	ds_read_b64_tr_b16 v[146:147], v121 offset:0x2800
	ds_read_b64_tr_b16 v[148:149], v121 offset:0x3000
	ds_read_b64_tr_b16 v[150:151], v121 offset:0x3800
	ds_read_b64_tr_b16 v[152:153], v121 offset:0x2200
	ds_read_b64_tr_b16 v[154:155], v121 offset:0x2a00
	ds_read_b64_tr_b16 v[156:157], v121 offset:0x3200
	ds_read_b64_tr_b16 v[158:159], v121 offset:0x3a00
	ds_read_b64_tr_b16 v[162:163], v121 offset:0x2400
	ds_read_b64_tr_b16 v[164:165], v121 offset:0x2c00
	ds_read_b64_tr_b16 v[166:167], v121 offset:0x3400
	ds_read_b64_tr_b16 v[168:169], v121 offset:0x3c00
	ds_read_b64_tr_b16 v[170:171], v121 offset:0x2600
	ds_read_b64_tr_b16 v[172:173], v121 offset:0x2e00
	ds_read_b64_tr_b16 v[174:175], v121 offset:0x3600
	ds_read_b64_tr_b16 v[176:177], v121 offset:0x3e00
	s_setprio 2
	v_exp_f32_e32 v64, v64
	v_exp_f32_e32 v65, v65
	v_exp_f32_e32 v66, v66
	v_exp_f32_e32 v67, v67
	v_exp_f32_e32 v68, v68
	v_exp_f32_e32 v69, v69
	v_add_f32_e32 v121, v65, v64
	v_exp_f32_e32 v70, v70
	v_add_f32_e32 v121, v66, v121
	v_exp_f32_e32 v71, v71
	v_add_f32_e32 v121, v67, v121
	v_exp_f32_e32 v72, v72
	v_add_f32_e32 v121, v68, v121
	v_exp_f32_e32 v73, v73
	v_add_f32_e32 v121, v69, v121
	v_exp_f32_e32 v74, v74
	v_add_f32_e32 v121, v70, v121
	v_exp_f32_e32 v75, v75
	v_add_f32_e32 v121, v71, v121
	v_exp_f32_e32 v76, v76
	v_add_f32_e32 v121, v72, v121
	v_exp_f32_e32 v77, v77
	v_add_f32_e32 v121, v73, v121
	v_exp_f32_e32 v78, v78
	v_add_f32_e32 v121, v74, v121
	v_exp_f32_e32 v79, v79
	v_add_f32_e32 v121, v75, v121
	v_add_f32_e32 v121, v76, v121
	v_add_f32_e32 v121, v77, v121
	v_add_f32_e32 v121, v78, v121
	v_add_f32_e32 v121, v79, v121
	v_add_f32_e32 v120, v120, v121
	v_cvt_pk_bf16_f32 v64, v64, v65
	v_cvt_pk_bf16_f32 v65, v66, v67
	v_cvt_pk_bf16_f32 v66, v68, v69
	v_cvt_pk_bf16_f32 v67, v70, v71
	v_cvt_pk_bf16_f32 v68, v72, v73
	v_cvt_pk_bf16_f32 v69, v74, v75
	v_cvt_pk_bf16_f32 v70, v76, v77
	v_cvt_pk_bf16_f32 v71, v78, v79
	s_nop 0
	v_permlane32_swap_b32_e32 v64, v66
	v_permlane32_swap_b32_e32 v65, v67
	v_permlane32_swap_b32_e32 v68, v70
	v_permlane32_swap_b32_e32 v69, v71
	s_waitcnt lgkmcnt(0)
	s_setprio 1
	s_cmp_lt_u32 s33, 0x100
	s_cbranch_scc1 .Lstg_d1_mid_19
	s_waitcnt vmcnt(3)
	s_barrier
	s_cmp_lg_u32 s7, 0xffffff00
	s_cbranch_scc0 .Lstg_d1_noearly
	s_add_i32 s99, s22, 0x2000
	s_and_b32 s99, s99, 0x6000
	s_add_i32 m0, s94, s99
	v_lshl_add_u64 v[196:197], v[100:101], 0, s[8:9]
	v_lshl_add_u64 v[198:199], v[102:103], 0, s[8:9]
	v_lshl_add_u64 v[200:201], v[104:105], 0, s[8:9]
	global_load_lds_dwordx4 v[196:197], off
	s_lshl_b32 s99, s23, 14
	s_add_i32 s99, s48, s99
	s_mov_b32 m0, s99
	s_nop 0
	global_load_lds_dwordx4 v[198:199], off
	s_add_i32 m0, s99, 0x400
	s_nop 0
	global_load_lds_dwordx4 v[200:201], off
.Lstg_d1_noearly:
.Lstg_d1_mid_19:
	v_mfma_f32_32x32x16_bf16 v[0:15], v[64:67], v[144:147], v[0:15]
	s_cmp_lt_i32 s0, s47
	s_cselect_b64 s[74:75], -1, 0
	s_cmp_ge_i32 s0, s52
	s_cselect_b64 s[90:91], -1, 0
	s_or_b64 s[74:75], s[74:75], s[90:91]
	s_and_b64 vcc, exec, s[74:75]
	v_mfma_f32_32x32x16_bf16 v[48:63], v[64:67], v[152:155], v[48:63]
	v_mfma_f32_32x32x16_bf16 v[16:31], v[64:67], v[162:165], v[16:31]
	v_mfma_f32_32x32x16_bf16 v[32:47], v[64:67], v[170:173], v[32:47]
	v_mfma_f32_32x32x16_bf16 v[0:15], v[68:71], v[148:151], v[0:15]
	v_mfma_f32_32x32x16_bf16 v[48:63], v[68:71], v[156:159], v[48:63]
	v_mfma_f32_32x32x16_bf16 v[16:31], v[68:71], v[166:169], v[16:31]
	v_mfma_f32_32x32x16_bf16 v[32:47], v[68:71], v[174:177], v[32:47]
	v_mfma_f32_32x32x16_bf16 v[64:79], v[124:127], v[92:95], 0
	v_mfma_f32_32x32x16_bf16 v[64:79], v[132:135], v[88:91], v[64:79]
	v_mfma_f32_32x32x16_bf16 v[64:79], v[136:139], v[84:87], v[64:79]
	v_mfma_f32_32x32x16_bf16 v[64:79], v[140:143], v[80:83], v[64:79]
	s_cbranch_vccnz .LBB0_1957
	v_add_u32_e32 v136, 0x28988, v122
	v_add_u32_e32 v138, 0x289a0, v122
	v_add_u32_e32 v140, 0x289a8, v122
	v_add_u32_e32 v123, 0x289c0, v122
	v_add_u32_e32 v124, 0x289c8, v122
	v_add_u32_e32 v126, 0x289e0, v122
	v_add_u32_e32 v132, 0x289e8, v122
	v_add_u32_e32 v121, 0x28980, v122
	ds_read2_b32 v[122:123], v123 offset1:1
	ds_read2_b32 v[124:125], v124 offset1:1
	ds_read2_b32 v[126:127], v126 offset1:1
	ds_read2_b32 v[132:133], v132 offset1:1
	ds_read2_b32 v[134:135], v121 offset1:1
	ds_read2_b32 v[136:137], v136 offset1:1
	ds_read2_b32 v[138:139], v138 offset1:1
	ds_read2_b32 v[140:141], v140 offset1:1
	s_waitcnt lgkmcnt(0)
	v_pk_add_f32 v[78:79], v[78:79], v[132:133]
	v_pk_add_f32 v[76:77], v[76:77], v[126:127]
	v_pk_add_f32 v[74:75], v[74:75], v[124:125]
	v_pk_add_f32 v[72:73], v[72:73], v[122:123]
	v_pk_add_f32 v[70:71], v[70:71], v[140:141]
	v_pk_add_f32 v[68:69], v[68:69], v[138:139]
	v_pk_add_f32 v[66:67], v[66:67], v[136:137]
	v_pk_add_f32 v[64:65], v[64:65], v[134:135]
